# v60 plus: P3 row loop software-pipelined one deep (next row loads staged before this row stores, into spare registers)
# baseline (speedup 1.0000x reference)
; __global__ void __launch_bounds__(NWAVES * 64, 2) mk_fwd(Params P) {
;     ...
;         const float sa = wave_sum(P.in[I_LQ1][lane] * P.in[I_LK1][lane]), sb = wave_sum(P.in[I_LQ2][lane] * P.in[I_LK2][lane]);
;         const float lam = __expf(sa) - __expf(sb) + 0.2f;
;         const f32x4 gs0 = *(const f32x4*)(P.in[I_GSUB] + (8 * lane) % 128), gs1 = *(const f32x4*)(P.in[I_GSUB] + (8 * lane) % 128 + 4);
;         const f32x4 gf0 = *(const f32x4*)(P.in[I_GFOX] + (8 * lane) % 64), gf1 = *(const f32x4*)(P.in[I_GFOX] + (8 * lane) % 64 + 4);
;         const int gw3 = (G > 64) ? (bx - 64) * NWAVES + wave : gw, NGW3 = (G > 64) ? (G - 64) * NWAVES : NGW;
;         const bool xal3 = (G == 256); const int m3start = xal3 ? (bx & 7) * SEQ + ((bx - 64) >> 3) * NWAVES + wave : gw3, m3step = xal3 ? 24 * NWAVES : NGW3, m3end = xal3 ? (bx & 7) * SEQ + SEQ : M;
;         if (G <= 64 || bx >= 64)
;         for (int m = m3start; m < m3end; m += m3step) {
;             const bf16* a = ATT + (size_t)m * NATT + 8 * lane;
;             const v4u o1 = *(const v4u*)a, o2 = *(const v4u*)(a + 512), of = *(const v4u*)(a + 1024);
.LBB0_845:
	v_readlane_b32 s8, v254, 6
	v_ashrrev_i32_e32 v129, 31, v128
	v_readlane_b32 s10, v254, 8
	v_readlane_b32 s11, v254, 9
	v_readlane_b32 s18, v254, 16
	v_readlane_b32 s19, v254, 17
	s_waitcnt lgkmcnt(0)
	v_lshlrev_b64 v[0:1], 2, v[128:129]
	v_readlane_b32 s12, v254, 10
	v_readlane_b32 s13, v254, 11
	v_readlane_b32 s14, v254, 12
	v_readlane_b32 s15, v254, 13
	v_readlane_b32 s20, v254, 18
	v_readlane_b32 s21, v254, 19
	s_mov_b64 s[10:11], s[18:19]
	v_readlane_b32 s22, v254, 20
	v_readlane_b32 s23, v254, 21
	s_mov_b64 s[12:13], s[20:21]
	v_lshl_add_u64 v[2:3], s[10:11], 0, v[0:1]
	v_readlane_b32 s9, v254, 7
	v_readlane_b32 s16, v254, 14
	v_readlane_b32 s17, v254, 15
	s_mov_b64 s[14:15], s[22:23]
	global_load_dword v4, v[2:3], off
	v_lshl_add_u64 v[2:3], s[12:13], 0, v[0:1]
	global_load_dword v5, v[2:3], off
	v_lshl_add_u64 v[2:3], s[14:15], 0, v[0:1]
	v_readlane_b32 s8, v254, 22
	v_readlane_b32 s9, v254, 23
	global_load_dword v2, v[2:3], off
	v_xor_b32_e32 v3, 1, v212
	v_lshl_add_u64 v[0:1], s[8:9], 0, v[0:1]
	global_load_dword v0, v[0:1], off
	v_and_b32_e32 v1, 64, v212
	v_add_u32_e32 v1, 64, v1
	v_xor_b32_e32 v6, 2, v212
	v_cmp_lt_i32_e32 vcc, v3, v1
	v_xor_b32_e32 v7, 4, v212
	v_xor_b32_e32 v8, 8, v212
	v_cndmask_b32_e32 v3, v212, v3, vcc
	v_cmp_lt_i32_e32 vcc, v6, v1
	v_lshlrev_b32_e32 v22, 2, v3
	s_lshl_b32 s2, s88, 3
	v_cndmask_b32_e32 v6, v212, v6, vcc
	v_cmp_lt_i32_e32 vcc, v7, v1
	v_lshlrev_b32_e32 v23, 2, v6
	s_add_i32 s2, s87, s2
	v_cndmask_b32_e32 v7, v212, v7, vcc
	v_lshlrev_b32_e32 v24, 2, v7
	v_cmp_lt_i32_e32 vcc, v8, v1
	s_add_i32 s8, s2, 0xfffffe00
	s_cmp_gt_i32 s82, 64
	v_cndmask_b32_e32 v8, v212, v8, vcc
	v_lshlrev_b32_e32 v25, 2, v8
	v_xor_b32_e32 v9, 16, v212
	s_cselect_b64 s[4:5], -1, 0
	v_cmp_lt_i32_e32 vcc, v9, v1
	s_and_b64 s[2:3], s[4:5], exec
	s_cselect_b32 s8, s8, s90
	v_cndmask_b32_e32 v9, v212, v9, vcc
	s_lshl_b32 s2, s88, 12
	v_lshlrev_b32_e32 v3, 2, v9
	s_and_b32 s3, s88, -8
	s_and_b32 s2, s2, 0x7000
	s_add_i32 s3, s3, s2
	v_readlane_b32 s12, v254, 26
	s_add_i32 s3, s3, s87
	v_xor_b32_e32 v10, 32, v212
	s_add_i32 s9, s2, 0x1000
	s_sub_i32 s12, s3, 64
	v_readlane_b32 s10, v254, 24
	v_readlane_b32 s11, v254, 25
	v_cmp_lt_i32_e32 vcc, v10, v1
	s_cmpk_eq_i32 s82, 0x100
	s_cselect_b64 s[10:11], -1, 0
	v_cndmask_b32_e32 v1, v212, v10, vcc
	v_lshlrev_b32_e32 v1, 2, v1
	s_and_b64 s[2:3], s[10:11], exec
	s_cselect_b32 s8, s12, s8
	s_cselect_b32 s2, s9, 0x8000
	s_and_b64 s[0:1], s[0:1], s[4:5]
	v_readlane_b32 s13, v254, 27
	s_cmp_ge_i32 s8, s2
	s_cselect_b64 s[12:13], -1, 0
	s_or_b64 s[0:1], s[0:1], s[12:13]
	s_and_b64 vcc, exec, s[0:1]
	v_readlane_b32 s14, v254, 28
	v_readlane_b32 s15, v254, 29
	v_readlane_b32 s16, v254, 30
	v_readlane_b32 s17, v254, 31
	v_readlane_b32 s18, v254, 32
	v_readlane_b32 s19, v254, 33
	v_readlane_b32 s20, v254, 34
	v_readlane_b32 s21, v254, 35
	v_readlane_b32 s22, v254, 36
	v_readlane_b32 s23, v254, 37
	s_waitcnt vmcnt(0)
	v_mul_f32_e32 v6, v4, v5
	ds_bpermute_b32 v6, v22, v6
	s_waitcnt lgkmcnt(0)
	v_fmac_f32_e32 v6, v4, v5
	v_mul_f32_e32 v7, v2, v0
	ds_bpermute_b32 v7, v22, v7
	s_waitcnt lgkmcnt(0)
	v_fmac_f32_e32 v7, v2, v0
	ds_bpermute_b32 v0, v23, v6
	ds_bpermute_b32 v2, v23, v7
	s_waitcnt lgkmcnt(1)
	v_add_f32_e32 v0, v6, v0
	s_waitcnt lgkmcnt(0)
	v_add_f32_e32 v2, v7, v2
	ds_bpermute_b32 v4, v24, v0
	ds_bpermute_b32 v5, v24, v2
	s_waitcnt lgkmcnt(1)
	v_add_f32_e32 v0, v0, v4
	s_waitcnt lgkmcnt(0)
	v_add_f32_e32 v2, v2, v5
	ds_bpermute_b32 v4, v25, v0
	ds_bpermute_b32 v5, v25, v2
	s_waitcnt lgkmcnt(1)
	v_add_f32_e32 v0, v0, v4
	s_waitcnt lgkmcnt(0)
	v_add_f32_e32 v2, v2, v5
	ds_bpermute_b32 v4, v3, v0
	ds_bpermute_b32 v3, v3, v2
	s_waitcnt lgkmcnt(1)
	v_add_f32_e32 v16, v0, v4
	s_waitcnt lgkmcnt(0)
	v_add_f32_e32 v17, v2, v3
	ds_bpermute_b32 v18, v1, v16
	ds_bpermute_b32 v19, v1, v17
	s_cbranch_vccnz .LBB0_848
	v_bfe_i32 v12, v128, 28, 1
	v_lshlrev_b32_e32 v20, 3, v128
	v_lshrrev_b32_e32 v2, 26, v12
	v_add_u32_e32 v2, v20, v2
	v_readlane_b32 s12, v254, 22
	v_and_b32_e32 v2, 0xffffffc0, v2
	v_readlane_b32 s16, v254, 26
	v_readlane_b32 s17, v254, 27
	v_sub_u32_e32 v2, v20, v2
	v_mov_b32_e32 v0, s16
	v_mov_b32_e32 v1, s17
	v_ashrrev_i32_e32 v3, 31, v2
	v_lshl_add_u64 v[10:11], v[2:3], 2, v[0:1]
	global_load_dwordx4 v[0:3], v[10:11], off offset:16
	global_load_dwordx4 v[4:7], v[10:11], off
	v_lshrrev_b32_e32 v10, 25, v12
	v_add_u32_e32 v10, v20, v10
	v_and_b32_e32 v10, 0xffffff80, v10
	v_readlane_b32 s14, v254, 24
	v_readlane_b32 s15, v254, 25
	v_sub_u32_e32 v10, v20, v10
	v_mov_b32_e32 v8, s14
	v_mov_b32_e32 v9, s15
	v_ashrrev_i32_e32 v11, 31, v10
	v_lshl_add_u64 v[26:27], v[10:11], 2, v[8:9]
	global_load_dwordx4 v[8:11], v[26:27], off
	global_load_dwordx4 v[12:15], v[26:27], off offset:16
	v_readlane_b32 s0, v254, 38
	v_readlane_b32 s1, v254, 39
	s_add_i32 s9, s0, 0xfffffe00
	s_mov_b32 s12, s0
	s_waitcnt lgkmcnt(1)
	v_add_f32_e32 v16, v16, v18
	s_waitcnt lgkmcnt(0)
	v_add_f32_e32 v17, v17, v19
	s_and_b64 s[0:1], s[4:5], exec
	v_mul_f32_e32 v16, 0x3fb8aa3b, v16
	v_mul_f32_e32 v17, 0x3fb8aa3b, v17
	s_cselect_b32 s4, s9, s12
	s_and_b64 s[0:1], s[10:11], exec
	v_exp_f32_e32 v18, v16
	v_exp_f32_e32 v19, v17
	s_cselect_b32 s10, 0xc0, s4
	s_ashr_i32 s9, s8, 31
	s_lshl_b64 s[0:1], s[8:9], 11
	v_readlane_b32 s13, v254, 23
	s_add_u32 s12, s72, s0
	s_addc_u32 s13, s73, s1
	s_ashr_i32 s11, s10, 31
	s_mul_i32 s16, s8, 0xc00
	v_sub_f32_e32 v18, v18, v19
	s_lshl_b64 s[14:15], s[10:11], 11
	v_readlane_b32 s18, v254, 28
	v_readlane_b32 s19, v254, 29
	v_readlane_b32 s20, v254, 30
	v_readlane_b32 s21, v254, 31
	s_mul_hi_i32 s17, s8, 0xc00
	v_ashrrev_i32_e32 v21, 31, v20
	v_add_f32_e32 v18, 0x3e4ccccd, v18
	s_add_u32 s16, s72, s16
	s_mov_b32 s3, 0xffff0000
	v_mov_b32_e32 v26, 0x3727c5ac
	s_mov_b32 s18, 0xf800000
	v_mov_b32_e32 v27, 0x260
	s_mov_b32 s19, 0x3f4ccccd
	s_movk_i32 s20, 0x7fff
	v_mov_b32_e32 v28, 0x358637bd
	v_lshlrev_b64 v[16:17], 1, v[20:21]
	s_mul_hi_i32 s9, s10, 0xc00
	s_mul_i32 s21, s10, 0xc00
	v_mov_b32_e32 v19, v18
	s_addc_u32 s17, s73, s17
	s_mov_b32 s11, 0x3800000
	v_readlane_b32 s22, v254, 32
	v_readlane_b32 s23, v254, 33
	v_readlane_b32 s24, v254, 34
	v_readlane_b32 s25, v254, 35
	v_readlane_b32 s26, v254, 36
	v_readlane_b32 s27, v254, 37
	s_waitcnt vmcnt(2)
	v_mov_b32_e32 v20, v5
	v_mov_b32_e32 v21, v7
	v_mov_b32_e32 v5, v6
	v_mov_b32_e32 v6, v1
	v_mov_b32_e32 v7, v3
	v_mov_b32_e32 v1, v2
	s_waitcnt vmcnt(1)
	v_mov_b32_e32 v2, v9
	v_mov_b32_e32 v3, v11
	v_mov_b32_e32 v9, v10
	s_waitcnt vmcnt(0)
	v_mov_b32_e32 v10, v13
	v_mov_b32_e32 v11, v15
	v_mov_b32_e32 v13, v14
	v_lshl_add_u64 v[74:75], s[16:17], 0, v[16:17]
	v_add_co_u32_e32 v74, vcc, 0x7800000, v74
	s_nop 1
	v_addc_co_u32_e32 v75, vcc, 0, v75, vcc
	global_load_dwordx4 v[62:65], v[74:75], off
	global_load_dwordx4 v[66:69], v[74:75], off offset:1024
	global_load_dwordx4 v[70:73], v[74:75], off offset:2048
	s_add_u32 s16, s16, s21
	s_addc_u32 s17, s17, s9
	s_waitcnt vmcnt(0)
; __global__ void __launch_bounds__(NWAVES * 64, 2) mk_fwd(Params P) {
;     ...
;         for (int m = m3start; m < m3end; m += m3step) {
;             const bf16* a = ATT + (size_t)m * NATT + 8 * lane;
;             const v4u o1 = *(const v4u*)a, o2 = *(const v4u*)(a + 512), of = *(const v4u*)(a + 1024);
;             float d[8], f[8];
; #pragma unroll
;             for (int e = 0; e < 4; ++e) { d[2 * e] = bflo(o1[e]) - lam * bflo(o2[e]); d[2 * e + 1] = bfhi(o1[e]) - lam * bfhi(o2[e]); f[2 * e] = bflo(of[e]); f[2 * e + 1] = bfhi(of[e]); }
;             float sd = 0.f, sf = 0.f;
; #pragma unroll
;             for (int e = 0; e < 8; ++e) { sd += d[e] * d[e]; sf += f[e] * f[e]; }
;             sd += __shfl_xor(sd, 1); sd += __shfl_xor(sd, 2); sd += __shfl_xor(sd, 4); sd += __shfl_xor(sd, 8);
;             sf += __shfl_xor(sf, 1); sf += __shfl_xor(sf, 2); sf += __shfl_xor(sf, 4);
.LBB0_847:
	s_add_i32 s8, s8, s10
	v_lshl_add_u64 v[42:43], s[12:13], 0, v[16:17]
	s_add_u32 s12, s12, s14
	s_addc_u32 s13, s13, s15
	s_waitcnt vmcnt(2)
	v_mov_b32_e32 v30, v62
	v_mov_b32_e32 v31, v63
	v_mov_b32_e32 v32, v64
	v_mov_b32_e32 v33, v65
	v_mov_b32_e32 v34, v66
	v_mov_b32_e32 v35, v67
	v_mov_b32_e32 v36, v68
	v_mov_b32_e32 v37, v69
	v_mov_b32_e32 v38, v70
	v_mov_b32_e32 v39, v71
	v_mov_b32_e32 v40, v72
	v_mov_b32_e32 v41, v73
	s_cmp_lt_i32 s8, s2
	s_cbranch_scc0 .Lp3_nostage
	v_lshl_add_u64 v[74:75], s[16:17], 0, v[16:17]
	v_add_co_u32_e32 v74, vcc, 0x7800000, v74
	s_nop 1
	v_addc_co_u32_e32 v75, vcc, 0, v75, vcc
	global_load_dwordx4 v[62:65], v[74:75], off
	global_load_dwordx4 v[66:69], v[74:75], off offset:1024
	global_load_dwordx4 v[70:73], v[74:75], off offset:2048
	s_add_u32 s16, s16, s21
	s_addc_u32 s17, s17, s9
.Lp3_nostage:
	s_cmp_lt_i32 s8, s2
	v_lshlrev_b32_e32 v15, 16, v31
	v_lshlrev_b32_e32 v14, 16, v30
	v_lshlrev_b32_e32 v45, 16, v35
	v_lshlrev_b32_e32 v44, 16, v34
	v_and_b32_e32 v31, 0xffff0000, v31
	v_and_b32_e32 v30, 0xffff0000, v30
	v_and_b32_e32 v35, 0xffff0000, v35
	v_and_b32_e32 v34, 0xffff0000, v34
	v_lshlrev_b32_e32 v47, 16, v33
	v_lshlrev_b32_e32 v46, 16, v32
	v_lshlrev_b32_e32 v49, 16, v37
	v_lshlrev_b32_e32 v48, 16, v36
	v_and_b32_e32 v33, 0xffff0000, v33
	v_and_b32_e32 v32, 0xffff0000, v32
	v_and_b32_e32 v37, 0xffff0000, v37
	v_and_b32_e32 v36, 0xffff0000, v36
	v_lshlrev_b32_e32 v51, 16, v39
	v_lshlrev_b32_e32 v50, 16, v38
	v_and_b32_e32 v39, 0xffff0000, v39
	v_and_b32_e32 v38, 0xffff0000, v38
	v_pk_fma_f32 v[14:15], v[18:19], v[44:45], v[14:15] neg_lo:[1,0,0] neg_hi:[1,0,0]
	v_pk_fma_f32 v[30:31], v[18:19], v[34:35], v[30:31] neg_lo:[1,0,0] neg_hi:[1,0,0]
	v_pk_fma_f32 v[32:33], v[18:19], v[36:37], v[32:33] neg_lo:[1,0,0] neg_hi:[1,0,0]
	v_pk_mul_f32 v[36:37], v[50:51], v[50:51]
	v_pk_mul_f32 v[44:45], v[38:39], v[38:39]
	v_lshlrev_b32_e32 v52, 16, v40
	v_and_b32_e32 v40, 0xffff0000, v40
	v_pk_mul_f32 v[54:55], v[14:15], v[14:15]
	v_pk_mul_f32 v[56:57], v[30:31], v[30:31]
	v_add_f32_e32 v29, v36, v44
	v_pk_fma_f32 v[34:35], v[18:19], v[48:49], v[46:47] neg_lo:[1,0,0] neg_hi:[1,0,0]
	v_mov_b32_e32 v46, v52
	v_mov_b32_e32 v47, v40
	v_add_f32_e32 v36, v54, v56
	v_add_f32_e32 v29, v29, v37
	v_lshlrev_b32_e32 v53, 16, v41
	v_and_b32_e32 v41, 0xffff0000, v41
	v_mov_b32_e32 v58, v34
	v_mov_b32_e32 v59, v32
	v_pk_mul_f32 v[46:47], v[46:47], v[46:47]
	v_add_f32_e32 v36, v36, v55
	v_add_f32_e32 v29, v29, v45
	v_mov_b32_e32 v48, v53
	v_mov_b32_e32 v49, v41
	v_pk_mul_f32 v[58:59], v[58:59], v[58:59]
	v_add_f32_e32 v36, v36, v57
	v_add_f32_e32 v29, v29, v46
	v_mov_b32_e32 v60, v35
	v_mov_b32_e32 v61, v33
	v_pk_mul_f32 v[48:49], v[48:49], v[48:49]
	v_add_f32_e32 v36, v36, v58
	v_add_f32_e32 v29, v29, v47
	v_pk_mul_f32 v[60:61], v[60:61], v[60:61]
	v_add_f32_e32 v36, v36, v59
	v_add_f32_e32 v29, v29, v48
	v_add_f32_e32 v36, v36, v60
	v_add_f32_e32 v29, v29, v49
	v_add_f32_e32 v36, v36, v61
	ds_bpermute_b32 v37, v22, v29
	ds_bpermute_b32 v44, v22, v36
	s_waitcnt lgkmcnt(1)
	v_add_f32_e32 v29, v29, v37
	s_waitcnt lgkmcnt(0)
	v_add_f32_e32 v36, v36, v44
	ds_bpermute_b32 v37, v23, v29
	ds_bpermute_b32 v44, v23, v36
	s_waitcnt lgkmcnt(1)
	v_add_f32_e32 v29, v29, v37
	s_waitcnt lgkmcnt(0)
	v_add_f32_e32 v36, v36, v44
	ds_bpermute_b32 v37, v24, v29
	ds_bpermute_b32 v44, v24, v36
	s_waitcnt lgkmcnt(1)
	v_add_f32_e32 v29, v29, v37
	s_waitcnt lgkmcnt(0)
	v_add_f32_e32 v36, v36, v44
	v_fmamk_f32 v29, v29, 0x3c800000, v28
	ds_bpermute_b32 v37, v25, v36
	v_mul_f32_e32 v44, 0x4f800000, v29
	v_cmp_gt_f32_e32 vcc, s18, v29
	s_waitcnt lgkmcnt(0)
; __device__ __forceinline__ unsigned pk2(float lo, float hi) { return f2bf(lo) | (f2bf(hi) << 16); }
; __global__ void __launch_bounds__(NWAVES * 64, 2) mk_fwd(Params P) {
;     ...
;             sd += __shfl_xor(sd, 1); sd += __shfl_xor(sd, 2); sd += __shfl_xor(sd, 4); sd += __shfl_xor(sd, 8);
;             sf += __shfl_xor(sf, 1); sf += __shfl_xor(sf, 2); sf += __shfl_xor(sf, 4);
;             const float rd = 0.8f / sqrtf(sd * (1.f / 128.f) + SUBLN_EPS), rf = 1.0f / sqrtf(sf * (1.f / 64.f) + EPS);
;             v4u wd, wf;
;             wd.x = pk2(d[0] * rd * gs0[0], d[1] * rd * gs0[1]); wd.y = pk2(d[2] * rd * gs0[2], d[3] * rd * gs0[3]); wd.z = pk2(d[4] * rd * gs1[0], d[5] * rd * gs1[1]); wd.w = pk2(d[6] * rd * gs1[2], d[7] * rd * gs1[3]);
;             wf.x = pk2(f[0] * rf * gf0[0], f[1] * rf * gf0[1]); wf.y = pk2(f[2] * rf * gf0[2], f[3] * rf * gf0[3]); wf.z = pk2(f[4] * rf * gf1[0], f[5] * rf * gf1[1]); wf.w = pk2(f[6] * rf * gf1[2], f[7] * rf * gf1[3]);
;             bf16* o = MIXA + (size_t)m * D + 8 * lane;
;             *(v4u*)o = wd; *(v4u*)(o + 512) = wf;
;         }
	v_add_f32_e32 v36, v36, v37
	v_cndmask_b32_e32 v29, v29, v44, vcc
	v_sqrt_f32_e32 v44, v29
	v_fmamk_f32 v36, v36, 0x3c000000, v26
	v_mul_f32_e32 v46, 0x4f800000, v36
	v_cmp_gt_f32_e64 s[0:1], s18, v36
	v_add_u32_e32 v37, -1, v44
	v_add_u32_e32 v45, 1, v44
	v_fma_f32 v47, -v37, v44, v29
	v_fma_f32 v48, -v45, v44, v29
	v_cndmask_b32_e64 v36, v36, v46, s[0:1]
	v_cmp_ge_f32_e64 s[4:5], 0, v47
	s_nop 1
	v_cndmask_b32_e64 v37, v44, v37, s[4:5]
	v_cmp_lt_f32_e64 s[4:5], 0, v48
	v_sqrt_f32_e32 v44, v36
	s_nop 0
	v_cndmask_b32_e64 v37, v37, v45, s[4:5]
	v_mul_f32_e32 v45, 0x37800000, v37
	v_cndmask_b32_e32 v37, v37, v45, vcc
	v_cmp_class_f32_e32 vcc, v29, v27
	v_add_u32_e32 v45, 1, v44
	v_fma_f32 v49, -v45, v44, v36
	v_cndmask_b32_e32 v29, v37, v29, vcc
	v_add_u32_e32 v37, -1, v44
	v_fma_f32 v48, -v37, v44, v36
	v_cmp_ge_f32_e32 vcc, 0, v48
	v_div_scale_f32 v46, s[4:5], v29, v29, 1.0
	s_nop 0
	v_cndmask_b32_e32 v37, v44, v37, vcc
	v_cmp_lt_f32_e32 vcc, 0, v49
	v_rcp_f32_e32 v54, v46
	v_div_scale_f32 v47, s[4:5], 1.0, v29, 1.0
	v_cndmask_b32_e32 v37, v37, v45, vcc
	v_mul_f32_e32 v44, 0x37800000, v37
	v_cndmask_b32_e64 v37, v37, v44, s[0:1]
	v_cmp_class_f32_e32 vcc, v36, v27
	v_fma_f32 v44, -v46, v54, 1.0
	v_fmac_f32_e32 v54, v44, v54
	v_cndmask_b32_e32 v36, v37, v36, vcc
	v_div_scale_f32 v37, s[0:1], v36, v36, s19
	v_rcp_f32_e32 v48, v37
	v_mul_f32_e32 v45, v47, v54
	v_fma_f32 v49, -v46, v45, v47
	v_fmac_f32_e32 v45, v49, v54
	v_fma_f32 v46, -v46, v45, v47
	v_fma_f32 v47, -v37, v48, 1.0
	v_div_scale_f32 v44, vcc, s19, v36, s19
	v_fmac_f32_e32 v48, v47, v48
	v_mul_f32_e32 v47, v44, v48
	v_fma_f32 v49, -v37, v47, v44
	v_fmac_f32_e32 v47, v49, v48
	v_fma_f32 v37, -v37, v47, v44
	v_div_fmas_f32 v37, v37, v48, v47
	s_mov_b64 vcc, s[4:5]
	v_div_fixup_f32 v36, v37, v36, s19
	v_div_fmas_f32 v37, v46, v54, v45
	v_pk_mul_f32 v[14:15], v[14:15], v[36:37] op_sel_hi:[1,0]
	v_pk_mul_f32 v[30:31], v[30:31], v[36:37] op_sel_hi:[1,0]
	v_pk_mul_f32 v[34:35], v[36:37], v[34:35] op_sel_hi:[0,1]
	v_pk_mul_f32 v[32:33], v[36:37], v[32:33] op_sel_hi:[0,1]
	v_div_fixup_f32 v36, v37, v29, 1.0
	v_pk_mul_f32 v[14:15], v[8:9], v[14:15]
	v_pk_mul_f32 v[30:31], v[2:3], v[30:31]
	v_pk_mul_f32 v[34:35], v[12:13], v[34:35]
	v_pk_mul_f32 v[32:33], v[10:11], v[32:33]
	v_pk_mul_f32 v[44:45], v[36:37], v[50:51] op_sel_hi:[0,1]
	v_pk_mul_f32 v[38:39], v[36:37], v[38:39] op_sel_hi:[0,1]
	v_pk_mul_f32 v[46:47], v[36:37], v[52:53] op_sel_hi:[0,1]
	v_pk_mul_f32 v[36:37], v[36:37], v[40:41] op_sel_hi:[0,1]
	v_bfe_u32 v29, v33, 16, 1
	v_bfe_u32 v49, v31, 16, 1
	v_bfe_u32 v50, v30, 16, 1
	v_bfe_u32 v51, v14, 16, 1
	v_bfe_u32 v52, v15, 16, 1
	v_bfe_u32 v53, v34, 16, 1
	v_bfe_u32 v54, v35, 16, 1
	v_pk_mul_f32 v[40:41], v[4:5], v[44:45]
	v_pk_mul_f32 v[44:45], v[0:1], v[46:47]
	v_pk_mul_f32 v[36:37], v[6:7], v[36:37]
	v_bfe_u32 v48, v32, 16, 1
	v_pk_mul_f32 v[38:39], v[20:21], v[38:39]
	v_add3_u32 v30, v30, v50, s20
	v_add3_u32 v31, v31, v49, s20
	v_add3_u32 v29, v33, v29, s20
	v_add3_u32 v33, v35, v54, s20
	v_add3_u32 v34, v34, v53, s20
	v_add3_u32 v15, v15, v52, s20
	v_add3_u32 v14, v14, v51, s20
	v_bfe_u32 v35, v37, 16, 1
	v_bfe_u32 v49, v40, 16, 1
	v_bfe_u32 v50, v41, 16, 1
	v_bfe_u32 v51, v44, 16, 1
	v_bfe_u32 v52, v45, 16, 1
	v_add_co_u32_e32 v42, vcc, s11, v42
	v_add3_u32 v32, v32, v48, s20
	v_bfe_u32 v46, v36, 16, 1
	v_bfe_u32 v47, v39, 16, 1
	v_bfe_u32 v48, v38, 16, 1
	v_lshrrev_b32_e32 v14, 16, v14
	v_lshrrev_b32_e32 v15, 16, v15
	v_lshrrev_b32_e32 v34, 16, v34
	v_lshrrev_b32_e32 v33, 16, v33
	v_add3_u32 v35, v37, v35, s20
	v_add3_u32 v37, v45, v52, s20
	v_add3_u32 v44, v44, v51, s20
	v_add3_u32 v41, v41, v50, s20
	v_add3_u32 v40, v40, v49, s20
	v_addc_co_u32_e32 v43, vcc, 0, v43, vcc
	v_add3_u32 v38, v38, v48, s20
	v_add3_u32 v39, v39, v47, s20
	v_add3_u32 v36, v36, v46, s20
	v_and_or_b32 v33, v29, s3, v33
	v_and_or_b32 v32, v32, s3, v34
	v_and_or_b32 v31, v31, s3, v15
	v_and_or_b32 v30, v30, s3, v14
	v_lshrrev_b32_e32 v14, 16, v40
	v_lshrrev_b32_e32 v15, 16, v41
	v_lshrrev_b32_e32 v29, 16, v44
	v_lshrrev_b32_e32 v34, 16, v37
	v_and_or_b32 v37, v35, s3, v34
	v_and_or_b32 v36, v36, s3, v29
	v_and_or_b32 v35, v39, s3, v15
	v_and_or_b32 v34, v38, s3, v14
	global_store_dwordx4 v[42:43], v[30:33], off
	global_store_dwordx4 v[42:43], v[34:37], off offset:1024
	s_cbranch_scc1 .LBB0_847
